# mode-1 K-loop balanced the same way (modes 0, 1, 3 now keep only M0 writes in the heavy load segments)
# baseline (speedup 1.0000x reference)
; #define PG8_STAGE(bufoff, gbase, voff) do { _Pragma("unroll") for (int _i = 0; _i < 2; ++_i) \
;         __builtin_amdgcn_global_load_lds((const unsigned*)((const char*)(gbase) + (voff)[_i]), (LAS unsigned*)(lds + (bufoff) + ldsw + _i * 8192), 16, 0, 0); } while (0)
; #define PG8_LDA(dst, b, h) do { _Pragma("unroll") for (int m = 0; m < 4; ++m) _Pragma("unroll") for (int k = 0; k < 2; ++k) dst[m][k] = *(const LAS bf16x8*)(lds + PG8_SA(b, h) + aoff + m * 2048 + k * 1024); } while (0)
; #define PG8_LDB(dst, b, h) do { _Pragma("unroll") for (int n = 0; n < 2; ++n) _Pragma("unroll") for (int k = 0; k < 2; ++k) dst[n][k] = *(const LAS bf16x8*)(lds + PG8_SB(b, h) + boff + n * 2048 + k * 1024); } while (0)
; #define PG8_MMA(ai, bj, At, Bt) do { __builtin_amdgcn_s_setprio(1); _Pragma("unroll") for (int m = 0; m < 4; ++m) _Pragma("unroll") for (int n = 0; n < 2; ++n) _Pragma("unroll") for (int k = 0; k < 2; ++k) \
;         acc[ai][bj][m][n] = __builtin_amdgcn_mfma_f32_16x16x32_bf16(Bt[n][k], At[m][k], acc[ai][bj][m][n], 0, 0, 0); __builtin_amdgcn_s_setprio(0); } while (0)
; #define PG8_WAIT_L(n) asm volatile("s_waitcnt lgkmcnt(" #n ")" ::: "memory")
; template <int MODE, class EpiT, class Sched>
; __device__ __forceinline__ void gemm_phase(LAS unsigned char* lds, const Gemm g, const Sched& S, const EpiT& E) {
;     ...
;         const bool has_next = S.next(ui + 1, nxt);
;         const char* nA = has_next ? (const char*)g.A + (size_t)nxt.pm * tstep : cA; const char* nB = has_next ? (const char*)g.Bt + (size_t)nxt.pn * tstep : cB;
;         for (int t = 0; t < nt; t += 2) {
;             const bool last = (t == nt - 2);
;             const char* a1 = cA + (size_t)(t + 1) * kstep;
;             const char* a2 = last ? nA : cA + (size_t)(t + 2) * kstep; const char* b2 = last ? nB : cB + (size_t)(t + 2) * kstep;
;             const char* a3 = a2 + kstep; const char* b3 = b2 + kstep;
;             PG8_LDB(B0, 0, 0); PG8_SCHED; PG8_LDA(At, 0, 0); PG8_STAGE(PG8_SA(1, 1), a1 + hstep, voffA);
;             PG8_WAIT_L(8); PG8_BAR; PG8_WAIT_L(0); PG8_MMA(0, 0, At, B0); PG8_BAR; PG8_SCHED;
;             PG8_LDB(B1, 0, 1); PG8_STAGE(PG8_SB(0, 0), b2, voffB);
;             PG8_BAR; PG8_WAIT_L(0); PG8_MMA(0, 1, At, B1); PG8_BAR;
;             PG8_LDA(At, 0, 1); PG8_STAGE(PG8_SA(0, 0), a2, voffA);
;             PG8_BAR; PG8_WAIT_L(0); PG8_MMA(1, 0, At, B0); PG8_BAR; PG8_SCHED;
.LBB0_279:
	s_mov_b32 s46, 0
	s_mov_b64 s[44:45], 0x100
	s_add_u32 s100, s10, s44
	s_addc_u32 s101, s11, s45
	s_add_u32 s52, s4, s44
	s_addc_u32 s53, s5, s45
	s_cmp_eq_u32 s60, 0
	s_cselect_b32 s46, s34, s100
	s_cselect_b32 s47, s35, s101
	s_cselect_b32 s53, s39, s53
	s_cselect_b32 s52, s38, s52
	s_add_u32 s98, s52, 0x80
	s_addc_u32 s99, s53, 0
	s_add_u32 s100, s100, s22
	s_addc_u32 s101, s101, 0
	s_sub_u32 s100, s100, 0x80
	s_subb_u32 s101, s101, 0
	s_mov_b32 s68, 0
	v_mov_b64_e32 v[130:131], v[150:151]
	v_mov_b64_e32 v[132:133], v[148:149]
.LBB0_280:
	s_add_i32 s68, s68, 2
	s_add_i32 s59, 0, 0x10000
	ds_read_b128 v[134:137], v250
	ds_read_b128 v[138:141], v250 offset:1024
	ds_read_b128 v[142:145], v250 offset:2048
	ds_read_b128 v[152:155], v250 offset:3072
	s_add_i32 m0, s30, 0xc000
	ds_read_b128 v[162:165], v160
	ds_read_b128 v[166:169], v160 offset:1024
	ds_read_b128 v[170:173], v160 offset:2048
	ds_read_b128 v[174:177], v160 offset:3072
	ds_read_b128 v[182:185], v160 offset:4096
	ds_read_b128 v[186:189], v160 offset:5120
	ds_read_b128 v[190:193], v160 offset:6144
	global_load_lds_dwordx4 v0, s[100:101]
	s_add_i32 m0, s30, 0xe000
	ds_read_b128 v[194:197], v160 offset:7168
	global_load_lds_dwordx4 v146, s[100:101]
	s_waitcnt lgkmcnt(8)
	s_barrier
	s_waitcnt lgkmcnt(0)
	v_mfma_f32_16x16x32_bf16 v[126:129], v[134:137], v[162:165], v[126:129]
	v_mfma_f32_16x16x32_bf16 v[122:125], v[142:145], v[162:165], v[122:125]
	v_mfma_f32_16x16x32_bf16 v[118:121], v[134:137], v[170:173], v[118:121]
	v_mfma_f32_16x16x32_bf16 v[114:117], v[142:145], v[170:173], v[114:117]
	v_mfma_f32_16x16x32_bf16 v[110:113], v[134:137], v[182:185], v[110:113]
	v_mfma_f32_16x16x32_bf16 v[106:109], v[142:145], v[182:185], v[106:109]
	v_mfma_f32_16x16x32_bf16 v[102:105], v[134:137], v[190:193], v[102:105]
	v_mfma_f32_16x16x32_bf16 v[98:101], v[142:145], v[190:193], v[98:101]
	v_mfma_f32_16x16x32_bf16 v[126:129], v[138:141], v[166:169], v[126:129]
	v_mfma_f32_16x16x32_bf16 v[122:125], v[152:155], v[166:169], v[122:125]
	v_mfma_f32_16x16x32_bf16 v[118:121], v[138:141], v[174:177], v[118:121]
	v_mfma_f32_16x16x32_bf16 v[114:117], v[152:155], v[174:177], v[114:117]
	v_mfma_f32_16x16x32_bf16 v[110:113], v[138:141], v[186:189], v[110:113]
	v_mfma_f32_16x16x32_bf16 v[106:109], v[152:155], v[186:189], v[106:109]
	v_mfma_f32_16x16x32_bf16 v[102:105], v[138:141], v[194:197], v[102:105]
	v_mfma_f32_16x16x32_bf16 v[98:101], v[152:155], v[194:197], v[98:101]
	s_barrier
	s_add_i32 s58, 0, 0x14000
	s_add_i32 s59, s59, s24
	s_mov_b32 m0, s59
	ds_read_b128 v[220:223], v250 offset:16384
	ds_read_b128 v[224:227], v250 offset:17408
	ds_read_b128 v[228:231], v250 offset:18432
	global_load_lds_dwordx4 v0, s[52:53]
	s_add_i32 m0, s59, 0x2000
	ds_read_b128 v[232:235], v250 offset:19456
	global_load_lds_dwordx4 v146, s[52:53]
	s_barrier
	s_waitcnt lgkmcnt(0)
	v_mfma_f32_16x16x32_bf16 v[94:97], v[220:223], v[162:165], v[94:97]
	v_mfma_f32_16x16x32_bf16 v[90:93], v[228:231], v[162:165], v[90:93]
	v_mfma_f32_16x16x32_bf16 v[86:89], v[220:223], v[170:173], v[86:89]
	v_mfma_f32_16x16x32_bf16 v[82:85], v[228:231], v[170:173], v[82:85]
	v_mfma_f32_16x16x32_bf16 v[78:81], v[220:223], v[182:185], v[78:81]
	v_mfma_f32_16x16x32_bf16 v[74:77], v[228:231], v[182:185], v[74:77]
	v_mfma_f32_16x16x32_bf16 v[70:73], v[220:223], v[190:193], v[70:73]
	v_mfma_f32_16x16x32_bf16 v[66:69], v[228:231], v[190:193], v[66:69]
	v_mfma_f32_16x16x32_bf16 v[94:97], v[224:227], v[166:169], v[94:97]
	v_mfma_f32_16x16x32_bf16 v[90:93], v[232:235], v[166:169], v[90:93]
	v_mfma_f32_16x16x32_bf16 v[86:89], v[224:227], v[174:177], v[86:89]
	v_mfma_f32_16x16x32_bf16 v[82:85], v[232:235], v[174:177], v[82:85]
	v_mfma_f32_16x16x32_bf16 v[78:81], v[224:227], v[186:189], v[78:81]
	v_mfma_f32_16x16x32_bf16 v[74:77], v[232:235], v[186:189], v[74:77]
	v_mfma_f32_16x16x32_bf16 v[70:73], v[224:227], v[194:197], v[70:73]
	v_mfma_f32_16x16x32_bf16 v[66:69], v[232:235], v[194:197], v[66:69]
	s_barrier
	s_mov_b32 m0, s30
	ds_read_b128 v[162:165], v160 offset:16384
	ds_read_b128 v[166:169], v160 offset:17408
	ds_read_b128 v[170:173], v160 offset:18432
	ds_read_b128 v[174:177], v160 offset:19456
	ds_read_b128 v[182:185], v160 offset:20480
	ds_read_b128 v[186:189], v160 offset:21504
	ds_read_b128 v[190:193], v160 offset:22528
	global_load_lds_dwordx4 v0, s[46:47]
	s_mov_b32 m0, s50
	ds_read_b128 v[194:197], v160 offset:23552
	global_load_lds_dwordx4 v146, s[46:47]
	s_barrier
	s_waitcnt lgkmcnt(0)
	v_mfma_f32_16x16x32_bf16 v[62:65], v[134:137], v[162:165], v[62:65]
	v_mfma_f32_16x16x32_bf16 v[58:61], v[142:145], v[162:165], v[58:61]
	v_mfma_f32_16x16x32_bf16 v[54:57], v[134:137], v[170:173], v[54:57]
	v_mfma_f32_16x16x32_bf16 v[50:53], v[142:145], v[170:173], v[50:53]
	v_mfma_f32_16x16x32_bf16 v[46:49], v[134:137], v[182:185], v[46:49]
	v_mfma_f32_16x16x32_bf16 v[42:45], v[142:145], v[182:185], v[42:45]
	v_mfma_f32_16x16x32_bf16 v[38:41], v[134:137], v[190:193], v[38:41]
	v_mfma_f32_16x16x32_bf16 v[34:37], v[142:145], v[190:193], v[34:37]
	v_mfma_f32_16x16x32_bf16 v[62:65], v[138:141], v[166:169], v[62:65]
	v_mfma_f32_16x16x32_bf16 v[58:61], v[152:155], v[166:169], v[58:61]
	v_mfma_f32_16x16x32_bf16 v[54:57], v[138:141], v[174:177], v[54:57]
	v_mfma_f32_16x16x32_bf16 v[50:53], v[152:155], v[174:177], v[50:53]
	v_mfma_f32_16x16x32_bf16 v[46:49], v[138:141], v[186:189], v[46:49]
	v_mfma_f32_16x16x32_bf16 v[42:45], v[152:155], v[186:189], v[42:45]
	v_mfma_f32_16x16x32_bf16 v[38:41], v[138:141], v[194:197], v[38:41]
	v_mfma_f32_16x16x32_bf16 v[34:37], v[152:155], v[194:197], v[34:37]
	s_barrier
; #define PG8_STAGE(bufoff, gbase, voff) do { _Pragma("unroll") for (int _i = 0; _i < 2; ++_i) \
;         __builtin_amdgcn_global_load_lds((const unsigned*)((const char*)(gbase) + (voff)[_i]), (LAS unsigned*)(lds + (bufoff) + ldsw + _i * 8192), 16, 0, 0); } while (0)
; #define PG8_LDA(dst, b, h) do { _Pragma("unroll") for (int m = 0; m < 4; ++m) _Pragma("unroll") for (int k = 0; k < 2; ++k) dst[m][k] = *(const LAS bf16x8*)(lds + PG8_SA(b, h) + aoff + m * 2048 + k * 1024); } while (0)
; #define PG8_LDB(dst, b, h) do { _Pragma("unroll") for (int n = 0; n < 2; ++n) _Pragma("unroll") for (int k = 0; k < 2; ++k) dst[n][k] = *(const LAS bf16x8*)(lds + PG8_SB(b, h) + boff + n * 2048 + k * 1024); } while (0)
; #define PG8_MMA(ai, bj, At, Bt) do { __builtin_amdgcn_s_setprio(1); _Pragma("unroll") for (int m = 0; m < 4; ++m) _Pragma("unroll") for (int n = 0; n < 2; ++n) _Pragma("unroll") for (int k = 0; k < 2; ++k) \
;         acc[ai][bj][m][n] = __builtin_amdgcn_mfma_f32_16x16x32_bf16(Bt[n][k], At[m][k], acc[ai][bj][m][n], 0, 0, 0); __builtin_amdgcn_s_setprio(0); } while (0)
; #define PG8_WAIT_V(n) asm volatile("s_waitcnt vmcnt(" #n ")" ::: "memory")
; #define PG8_WAIT_L(n) asm volatile("s_waitcnt lgkmcnt(" #n ")" ::: "memory")
; #define PG8_BAR __builtin_amdgcn_s_barrier()
; #define PG8_SCHED __builtin_amdgcn_sched_barrier(0)
; template <int MODE, class EpiT, class Sched>
; __device__ __forceinline__ void gemm_phase(LAS unsigned char* lds, const Gemm g, const Sched& S, const EpiT& E) {
;     ...
;             PG8_BAR; PG8_WAIT_L(0); PG8_MMA(1, 0, At, B0); PG8_BAR; PG8_SCHED;
;             PG8_STAGE(PG8_SB(0, 1), b2 + hstep, voffB);
;             PG8_WAIT_V(6); PG8_BAR; PG8_MMA(1, 1, At, B1); PG8_BAR;
;             PG8_LDB(B0, 1, 0); PG8_SCHED; PG8_LDA(At, 1, 0); PG8_STAGE(PG8_SA(0, 1), a2 + hstep, voffA);
;             PG8_WAIT_L(8); PG8_BAR; PG8_WAIT_L(0); PG8_MMA(0, 0, At, B0); PG8_BAR; PG8_SCHED;
;             PG8_LDB(B1, 1, 1); PG8_STAGE(PG8_SB(1, 0), b3, voffB);
;             PG8_BAR; PG8_WAIT_L(0); PG8_MMA(0, 1, At, B1); PG8_BAR;
	s_add_u32 s100, s46, 0x80
	s_addc_u32 s101, s47, 0
	s_add_u32 s46, s46, s22
	s_addc_u32 s47, s47, 0
	s_add_u32 s52, s52, s22
	s_addc_u32 s53, s53, 0
	s_add_i32 s58, s58, s24
	s_mov_b32 m0, s58
	s_nop 0
	global_load_lds_dwordx4 v0, s[52:53]
	s_add_i32 m0, s58, 0x2000
	s_nop 0
	global_load_lds_dwordx4 v146, s[52:53]
	s_add_u32 s44, s44, 0x100
	s_addc_u32 s45, s45, 0
	s_waitcnt vmcnt(6)
	s_barrier
	v_mfma_f32_16x16x32_bf16 v[30:33], v[220:223], v[162:165], v[30:33]
	v_mfma_f32_16x16x32_bf16 v[26:29], v[228:231], v[162:165], v[26:29]
	v_mfma_f32_16x16x32_bf16 v[22:25], v[220:223], v[170:173], v[22:25]
	v_mfma_f32_16x16x32_bf16 v[18:21], v[228:231], v[170:173], v[18:21]
	v_mfma_f32_16x16x32_bf16 v[14:17], v[220:223], v[182:185], v[14:17]
	v_mfma_f32_16x16x32_bf16 v[10:13], v[228:231], v[182:185], v[10:13]
	v_mfma_f32_16x16x32_bf16 v[6:9], v[220:223], v[190:193], v[6:9]
	v_mfma_f32_16x16x32_bf16 v[2:5], v[228:231], v[190:193], v[2:5]
	v_mfma_f32_16x16x32_bf16 v[30:33], v[224:227], v[166:169], v[30:33]
	v_mfma_f32_16x16x32_bf16 v[26:29], v[232:235], v[166:169], v[26:29]
	v_mfma_f32_16x16x32_bf16 v[22:25], v[224:227], v[174:177], v[22:25]
	v_mfma_f32_16x16x32_bf16 v[18:21], v[232:235], v[174:177], v[18:21]
	v_mfma_f32_16x16x32_bf16 v[14:17], v[224:227], v[186:189], v[14:17]
	v_mfma_f32_16x16x32_bf16 v[10:13], v[232:235], v[186:189], v[10:13]
	v_mfma_f32_16x16x32_bf16 v[6:9], v[224:227], v[194:197], v[6:9]
	v_mfma_f32_16x16x32_bf16 v[2:5], v[232:235], v[194:197], v[2:5]
	s_barrier
	s_add_i32 s52, 0, 0x18000
	ds_read_b128 v[134:137], v250 offset:32768
	ds_read_b128 v[138:141], v250 offset:33792
	ds_read_b128 v[142:145], v250 offset:34816
	ds_read_b128 v[152:155], v250 offset:35840
	s_mov_b32 m0, s51
	ds_read_b128 v[162:165], v160 offset:32768
	ds_read_b128 v[166:169], v160 offset:33792
	ds_read_b128 v[170:173], v160 offset:34816
	ds_read_b128 v[174:177], v160 offset:35840
	ds_read_b128 v[182:185], v160 offset:36864
	ds_read_b128 v[186:189], v160 offset:37888
	ds_read_b128 v[190:193], v160 offset:38912
	global_load_lds_dwordx4 v0, s[46:47]
	s_mov_b32 m0, s54
	ds_read_b128 v[194:197], v160 offset:39936
	global_load_lds_dwordx4 v146, s[46:47]
	s_waitcnt lgkmcnt(8)
	s_barrier
	s_waitcnt lgkmcnt(0)
	v_mfma_f32_16x16x32_bf16 v[126:129], v[134:137], v[162:165], v[126:129]
	v_mfma_f32_16x16x32_bf16 v[122:125], v[142:145], v[162:165], v[122:125]
	v_mfma_f32_16x16x32_bf16 v[118:121], v[134:137], v[170:173], v[118:121]
	v_mfma_f32_16x16x32_bf16 v[114:117], v[142:145], v[170:173], v[114:117]
	v_mfma_f32_16x16x32_bf16 v[110:113], v[134:137], v[182:185], v[110:113]
	v_mfma_f32_16x16x32_bf16 v[106:109], v[142:145], v[182:185], v[106:109]
	v_mfma_f32_16x16x32_bf16 v[102:105], v[134:137], v[190:193], v[102:105]
	v_mfma_f32_16x16x32_bf16 v[98:101], v[142:145], v[190:193], v[98:101]
	v_mfma_f32_16x16x32_bf16 v[126:129], v[138:141], v[166:169], v[126:129]
	v_mfma_f32_16x16x32_bf16 v[122:125], v[152:155], v[166:169], v[122:125]
	v_mfma_f32_16x16x32_bf16 v[118:121], v[138:141], v[174:177], v[118:121]
	v_mfma_f32_16x16x32_bf16 v[114:117], v[152:155], v[174:177], v[114:117]
	v_mfma_f32_16x16x32_bf16 v[110:113], v[138:141], v[186:189], v[110:113]
	v_mfma_f32_16x16x32_bf16 v[106:109], v[152:155], v[186:189], v[106:109]
	v_mfma_f32_16x16x32_bf16 v[102:105], v[138:141], v[194:197], v[102:105]
	v_mfma_f32_16x16x32_bf16 v[98:101], v[152:155], v[194:197], v[98:101]
	s_barrier
	s_add_i32 s46, 0, 0x1c000
	s_add_i32 s47, s52, s24
	s_mov_b32 m0, s47
	ds_read_b128 v[220:223], v250 offset:49152
	ds_read_b128 v[224:227], v250 offset:50176
	ds_read_b128 v[228:231], v250 offset:51200
	global_load_lds_dwordx4 v0, s[98:99]
	s_add_i32 m0, s47, 0x2000
	ds_read_b128 v[232:235], v250 offset:52224
	global_load_lds_dwordx4 v146, s[98:99]
	s_barrier
	s_waitcnt lgkmcnt(0)
	v_mfma_f32_16x16x32_bf16 v[94:97], v[220:223], v[162:165], v[94:97]
	v_mfma_f32_16x16x32_bf16 v[90:93], v[228:231], v[162:165], v[90:93]
	v_mfma_f32_16x16x32_bf16 v[86:89], v[220:223], v[170:173], v[86:89]
	v_mfma_f32_16x16x32_bf16 v[82:85], v[228:231], v[170:173], v[82:85]
	v_mfma_f32_16x16x32_bf16 v[78:81], v[220:223], v[182:185], v[78:81]
	v_mfma_f32_16x16x32_bf16 v[74:77], v[228:231], v[182:185], v[74:77]
	v_mfma_f32_16x16x32_bf16 v[70:73], v[220:223], v[190:193], v[70:73]
	v_mfma_f32_16x16x32_bf16 v[66:69], v[228:231], v[190:193], v[66:69]
	v_mfma_f32_16x16x32_bf16 v[94:97], v[224:227], v[166:169], v[94:97]
	v_mfma_f32_16x16x32_bf16 v[90:93], v[232:235], v[166:169], v[90:93]
	v_mfma_f32_16x16x32_bf16 v[86:89], v[224:227], v[174:177], v[86:89]
	v_mfma_f32_16x16x32_bf16 v[82:85], v[232:235], v[174:177], v[82:85]
	v_mfma_f32_16x16x32_bf16 v[78:81], v[224:227], v[186:189], v[78:81]
	v_mfma_f32_16x16x32_bf16 v[74:77], v[232:235], v[186:189], v[74:77]
	v_mfma_f32_16x16x32_bf16 v[70:73], v[224:227], v[194:197], v[70:73]
	v_mfma_f32_16x16x32_bf16 v[66:69], v[232:235], v[194:197], v[66:69]
	s_barrier
; #define PG8_STAGE(bufoff, gbase, voff) do { _Pragma("unroll") for (int _i = 0; _i < 2; ++_i) \
;         __builtin_amdgcn_global_load_lds((const unsigned*)((const char*)(gbase) + (voff)[_i]), (LAS unsigned*)(lds + (bufoff) + ldsw + _i * 8192), 16, 0, 0); } while (0)
; #define PG8_LDA(dst, b, h) do { _Pragma("unroll") for (int m = 0; m < 4; ++m) _Pragma("unroll") for (int k = 0; k < 2; ++k) dst[m][k] = *(const LAS bf16x8*)(lds + PG8_SA(b, h) + aoff + m * 2048 + k * 1024); } while (0)
; #define PG8_MMA(ai, bj, At, Bt) do { __builtin_amdgcn_s_setprio(1); _Pragma("unroll") for (int m = 0; m < 4; ++m) _Pragma("unroll") for (int n = 0; n < 2; ++n) _Pragma("unroll") for (int k = 0; k < 2; ++k) \
;         acc[ai][bj][m][n] = __builtin_amdgcn_mfma_f32_16x16x32_bf16(Bt[n][k], At[m][k], acc[ai][bj][m][n], 0, 0, 0); __builtin_amdgcn_s_setprio(0); } while (0)
; #define PG8_WAIT_V(n) asm volatile("s_waitcnt vmcnt(" #n ")" ::: "memory")
; #define PG8_WAIT_L(n) asm volatile("s_waitcnt lgkmcnt(" #n ")" ::: "memory")
; #define PG8_BAR __builtin_amdgcn_s_barrier()
; #define PG8_SCHED __builtin_amdgcn_sched_barrier(0)
;     template <int mode> __device__ __forceinline__ void run(const f32x4 (&acc)[2][2][4][2], const Unit& u, int wr, int wc, int fr, int fq, const LAS float* sc) const {
;     ...
;             const int col0 = u.pn * BM + wc * 32 + 8 * fq;
;             f32x4 bv[2][2];
; #pragma unroll
;             for (int bj = 0; bj < 2; ++bj)
; #pragma unroll
;                 for (int n = 0; n < 2; ++n) bv[bj][n] = bias ? *(const f32x4*)(bias + col0 + bj * HALF + 4 * n) : (f32x4){0.f, 0.f, 0.f, 0.f};
; template <int MODE, class EpiT, class Sched>
; __device__ __forceinline__ void gemm_phase(LAS unsigned char* lds, const Gemm g, const Sched& S, const EpiT& E) {
;     ...
;             PG8_LDA(At, 1, 1); PG8_STAGE(PG8_SA(1, 0), a3, voffA);
;             PG8_BAR; PG8_WAIT_L(0); PG8_MMA(1, 0, At, B0); PG8_BAR; PG8_SCHED;
;             PG8_STAGE(PG8_SB(1, 1), b3 + hstep, voffB);
;             PG8_WAIT_V(6); PG8_BAR; PG8_MMA(1, 1, At, B1); PG8_BAR;
	s_mov_b32 m0, s56
	ds_read_b128 v[162:165], v160 offset:49152
	ds_read_b128 v[166:169], v160 offset:50176
	ds_read_b128 v[170:173], v160 offset:51200
	ds_read_b128 v[174:177], v160 offset:52224
	ds_read_b128 v[182:185], v160 offset:53248
	ds_read_b128 v[186:189], v160 offset:54272
	ds_read_b128 v[190:193], v160 offset:55296
	global_load_lds_dwordx4 v0, s[100:101]
	s_mov_b32 m0, s57
	ds_read_b128 v[194:197], v160 offset:56320
	global_load_lds_dwordx4 v146, s[100:101]
	s_barrier
	s_waitcnt lgkmcnt(0)
	v_mfma_f32_16x16x32_bf16 v[62:65], v[134:137], v[162:165], v[62:65]
	v_mfma_f32_16x16x32_bf16 v[58:61], v[142:145], v[162:165], v[58:61]
	v_mfma_f32_16x16x32_bf16 v[54:57], v[134:137], v[170:173], v[54:57]
	v_mfma_f32_16x16x32_bf16 v[50:53], v[142:145], v[170:173], v[50:53]
	v_mfma_f32_16x16x32_bf16 v[46:49], v[134:137], v[182:185], v[46:49]
	v_mfma_f32_16x16x32_bf16 v[42:45], v[142:145], v[182:185], v[42:45]
	v_mfma_f32_16x16x32_bf16 v[38:41], v[134:137], v[190:193], v[38:41]
	v_mfma_f32_16x16x32_bf16 v[34:37], v[142:145], v[190:193], v[34:37]
	v_mfma_f32_16x16x32_bf16 v[62:65], v[138:141], v[166:169], v[62:65]
	v_mfma_f32_16x16x32_bf16 v[58:61], v[152:155], v[166:169], v[58:61]
	v_mfma_f32_16x16x32_bf16 v[54:57], v[138:141], v[174:177], v[54:57]
	v_mfma_f32_16x16x32_bf16 v[50:53], v[152:155], v[174:177], v[50:53]
	v_mfma_f32_16x16x32_bf16 v[46:49], v[138:141], v[186:189], v[46:49]
	v_mfma_f32_16x16x32_bf16 v[42:45], v[152:155], v[186:189], v[42:45]
	v_mfma_f32_16x16x32_bf16 v[38:41], v[138:141], v[194:197], v[38:41]
	v_mfma_f32_16x16x32_bf16 v[34:37], v[152:155], v[194:197], v[34:37]
	s_barrier
	s_add_i32 s46, s46, s24
	s_add_u32 s98, s98, s22
	s_addc_u32 s99, s99, 0
	s_mov_b32 m0, s46
	s_nop 0
	global_load_lds_dwordx4 v0, s[98:99]
	s_add_i32 m0, s46, 0x2000
	s_nop 0
	global_load_lds_dwordx4 v146, s[98:99]
	s_add_u32 s100, s10, s44
	s_addc_u32 s101, s11, s45
	s_add_u32 s52, s4, s44
	s_addc_u32 s53, s5, s45
	s_cmp_eq_u32 s60, s68
	s_cselect_b32 s46, s34, s100
	s_cselect_b32 s47, s35, s101
	s_cselect_b32 s53, s39, s53
	s_cselect_b32 s52, s38, s52
	s_add_u32 s98, s52, 0x80
	s_addc_u32 s99, s53, 0
	s_add_u32 s100, s100, s22
	s_addc_u32 s101, s101, 0
	s_sub_u32 s100, s100, 0x80
	s_subb_u32 s101, s101, 0
	s_waitcnt vmcnt(6)
	s_barrier
	v_mfma_f32_16x16x32_bf16 v[30:33], v[220:223], v[162:165], v[30:33]
	v_mfma_f32_16x16x32_bf16 v[26:29], v[228:231], v[162:165], v[26:29]
	v_mfma_f32_16x16x32_bf16 v[22:25], v[220:223], v[170:173], v[22:25]
	v_mfma_f32_16x16x32_bf16 v[18:21], v[228:231], v[170:173], v[18:21]
	v_mfma_f32_16x16x32_bf16 v[14:17], v[220:223], v[182:185], v[14:17]
	v_mfma_f32_16x16x32_bf16 v[10:13], v[228:231], v[182:185], v[10:13]
	v_mfma_f32_16x16x32_bf16 v[6:9], v[220:223], v[190:193], v[6:9]
	v_mfma_f32_16x16x32_bf16 v[2:5], v[228:231], v[190:193], v[2:5]
	v_mfma_f32_16x16x32_bf16 v[30:33], v[224:227], v[166:169], v[30:33]
	v_mfma_f32_16x16x32_bf16 v[26:29], v[232:235], v[166:169], v[26:29]
	v_mfma_f32_16x16x32_bf16 v[22:25], v[224:227], v[174:177], v[22:25]
	v_mfma_f32_16x16x32_bf16 v[18:21], v[232:235], v[174:177], v[18:21]
	v_mfma_f32_16x16x32_bf16 v[14:17], v[224:227], v[186:189], v[14:17]
	v_mfma_f32_16x16x32_bf16 v[10:13], v[232:235], v[186:189], v[10:13]
	v_mfma_f32_16x16x32_bf16 v[6:9], v[224:227], v[194:197], v[6:9]
	v_mfma_f32_16x16x32_bf16 v[2:5], v[232:235], v[194:197], v[2:5]
	s_barrier
	s_cmp_ge_u32 s68, s55
	s_cbranch_scc0 .LBB0_280
	v_lshl_or_b32 v152, s3, 8, v159
	v_ashrrev_i32_e32 v153, 31, v152
	v_cndmask_b32_e64 v131, 0, 1, s[28:29]
	v_lshl_add_u64 v[154:155], v[152:153], 2, s[12:13]
	v_mov_b32_e32 v130, 0
	v_cmp_ne_u32_e64 s[44:45], 1, v131
	s_andn2_b64 vcc, exec, s[28:29]
	v_mov_b32_e32 v134, 0
	v_mov_b32_e32 v135, 0
	v_mov_b32_e32 v136, 0
	v_mov_b32_e32 v137, 0
	s_cbranch_vccnz .LBB0_283
	global_load_dwordx4 v[134:137], v[154:155], off
